# attention steady loop: one static s_setprio 1 for waves 4-7 before the loop, all per-phase s_setprio toggles in the loop removed
# baseline (speedup 1.0000x reference)
.LBB0_841:
	s_ashr_i32 s4, s74, 9
	s_lshl_b32 s1, s74, 8
	s_lshl_b32 s0, s4, 13
	s_and_b32 s1, s1, 0x1f00
	s_or_b32 s0, s0, s1
	s_ashr_i32 s1, s0, 31
	s_lshl_b32 s5, s74, 1
	s_lshl_b64 s[8:9], s[0:1], 10
	s_and_b32 s80, s5, 0x380
	s_lshl_b64 s[0:1], s[0:1], 11
	s_add_u32 s0, s30, s0
	s_addc_u32 s1, s31, s1
	s_lshl_b32 s5, s74, 2
	s_and_b32 s5, s5, 0x780
	s_add_u32 s12, s0, s5
	s_addc_u32 s13, s1, 0
	s_mul_i32 s1, s4, 0x1080000
	s_mul_hi_i32 s0, s4, 0x1080000
	s_add_u32 s6, s35, s1
	s_addc_u32 s7, s54, s0
	s_add_u32 s6, s6, s5
	s_addc_u32 s7, s7, 0
	s_add_u32 s1, s55, s1
	s_addc_u32 s0, s60, s0
	s_lshl_b32 s5, s80, 1
	v_mov_b32_e32 v12, v223
	s_add_u32 s14, s1, s5
	s_addc_u32 s15, s0, 0
	v_readfirstlane_b32 s5, v12
	s_ashr_i32 s75, s5, 6
	s_lshl_b32 s0, s75, 5
	s_ashr_i32 s1, s0, 31
	s_lshl_b64 s[10:11], s[0:1], 10
	s_lshl_b64 s[0:1], s[0:1], 11
	v_and_b32_e32 v213, 63, v12
	s_add_u32 s22, s12, s0
	s_addc_u32 s23, s13, s1
	v_lshlrev_b32_e32 v208, 11, v213
	s_lshl_b32 s12, s75, 3
	v_lshl_add_u64 v[0:1], s[6:7], 0, v[208:209]
	s_ashr_i32 s13, s12, 31
	v_lshl_add_u64 v[204:205], s[12:13], 1, v[0:1]
	s_lshl_b32 s1, s75, 4
	v_bfe_u32 v0, v12, 2, 4
	v_and_or_b32 v0, s1, 48, v0
	s_ashr_i32 s1, s5, 3
	s_and_b32 s6, s1, 0xffffffe0
	s_and_b32 s0, s5, 0x3fffffc0
	s_ashr_i32 s7, s6, 31
	s_lshl_b32 s1, s75, 10
	v_lshlrev_b32_e32 v0, 11, v0
	v_mov_b32_e32 v1, v209
	v_lshlrev_b32_e32 v218, 3, v12
	s_cmp_lg_u32 0, -1
	v_lshl_add_u64 v[0:1], s[14:15], 0, v[0:1]
	v_and_b32_e32 v219, 24, v218
	s_cselect_b32 s5, 0, 0
	v_lshl_add_u64 v[0:1], s[6:7], 1, v[0:1]
	v_lshlrev_b32_e32 v2, 1, v219
	v_mov_b32_e32 v3, v209
	s_add_i32 s26, s1, s5
	s_mov_b32 s1, m0
	s_mov_b32 m0, s26
	s_nop 0
	global_load_lds_dwordx4 v[204:205], off
	s_mov_b32 m0, s1
	v_bfe_u32 v217, v12, 5, 1
	v_lshl_add_u64 v[224:225], v[0:1], 0, v[2:3]
	s_add_i32 s27, s26, 0x6000
	s_mov_b32 s1, m0
	s_mov_b32 m0, s27
	s_nop 0
	global_load_lds_dwordx4 v[224:225], off
	s_mov_b32 m0, s1
	v_and_b32_e32 v216, 31, v12
	v_lshl_add_u64 v[226:227], v[224:225], 0, s[92:93]
	s_add_i32 s1, s26, 0x8000
	s_mov_b32 s5, m0
	s_mov_b32 m0, s1
	s_nop 0
	global_load_lds_dwordx4 v[226:227], off
	s_mov_b32 m0, s5
	v_lshl_add_u64 v[0:1], v[204:205], 0, s[58:59]
	v_lshlrev_b32_e32 v221, 4, v217
	s_add_i32 s1, s26, 0x2000
	s_mov_b32 s5, m0
	s_mov_b32 m0, s1
	s_nop 0
	global_load_lds_dwordx4 v[0:1], off
	s_mov_b32 m0, s5
	v_lshl_or_b32 v0, v216, 11, v221
	global_load_dwordx4 v[156:159], v0, s[22:23]
	global_load_dwordx4 v[152:155], v0, s[22:23] offset:32
	global_load_dwordx4 v[148:151], v0, s[22:23] offset:64
	global_load_dwordx4 v[144:147], v0, s[22:23] offset:96
	v_lshlrev_b32_e32 v0, 10, v217
	v_lshlrev_b32_e32 v1, 4, v216
	v_add3_u32 v214, 0, v0, v1
	v_lshl_add_u64 v[0:1], v[204:205], 0, s[90:91]
	s_add_i32 s1, s26, 0x4000
	s_mov_b32 s5, m0
	s_mov_b32 m0, s1
	s_nop 0
	global_load_lds_dwordx4 v[0:1], off
	s_mov_b32 m0, s5
	s_waitcnt vmcnt(4) lgkmcnt(0)
	s_barrier
	ds_read_b128 v[0:3], v214
	ds_read_b128 v[4:7], v214 offset:512
	s_mov_b32 s36, 0
	s_mov_b32 s37, s36
	s_mov_b32 s38, s36
	s_mov_b32 s39, s36
	s_mov_b32 s40, s36
	s_mov_b32 s41, s36
	s_mov_b32 s42, s36
	s_mov_b32 s43, s36
	s_mov_b32 s44, s36
	s_mov_b32 s45, s36
	s_mov_b32 s46, s36
	s_mov_b32 s47, s36
	s_mov_b32 s48, s36
	s_mov_b32 s49, s36
	s_mov_b32 s50, s36
	s_mov_b32 s51, s36
	v_lshlrev_b32_e32 v52, 1, v12
	v_lshlrev_b32_e32 v53, 4, v12
	s_lshl_b32 s0, s0, 2
	v_and_b32_e32 v210, 32, v52
	v_and_b32_e32 v52, 0xc0, v53
	v_lshl_or_b32 v220, v217, 8, v52
	v_add_u32_e32 v52, 0, v210
	v_add3_u32 v211, v52, v219, v220
	s_mov_b32 s5, -1
	s_movk_i32 s23, 0x2000
	s_waitcnt vmcnt(0) lgkmcnt(0)
	v_mfma_f32_32x32x16_bf16 v[32:47], v[0:3], v[156:159], 0
	s_movk_i32 s22, 0x4000
	v_cmp_gt_u32_e64 s[6:7], 32, v213
	v_lshl_add_u64 v[228:229], v[224:225], 0, s[18:19]
	v_mov_b32_e32 v215, 0
	v_mfma_f32_32x32x16_bf16 v[16:31], v[4:7], v[156:159], 0
	ds_read_b128 v[0:3], v214 offset:2048
	ds_read_b128 v[4:7], v214 offset:2560
	s_waitcnt lgkmcnt(1)
	v_mfma_f32_32x32x16_bf16 v[32:47], v[0:3], v[152:155], v[32:47]
	ds_read_b128 v[0:3], v214 offset:4608
	ds_read_b128 v[8:11], v214 offset:4096
	s_waitcnt lgkmcnt(2)
	v_mfma_f32_32x32x16_bf16 v[16:31], v[4:7], v[152:155], v[16:31]
	ds_read_b128 v[48:51], v214 offset:6656
	ds_read_b128 v[4:7], v214 offset:6144
	s_waitcnt lgkmcnt(2)
	v_mfma_f32_32x32x16_bf16 v[32:47], v[8:11], v[148:151], v[32:47]
	v_mfma_f32_32x32x16_bf16 v[16:31], v[0:3], v[148:151], v[16:31]
	s_waitcnt lgkmcnt(0)
	v_mfma_f32_32x32x16_bf16 v[32:47], v[4:7], v[144:147], v[32:47]
	v_mov_b64_e32 v[0:1], s[36:37]
	v_mov_b64_e32 v[2:3], s[38:39]
	v_mov_b64_e32 v[4:5], s[40:41]
	v_mov_b64_e32 v[6:7], s[42:43]
	v_mov_b64_e32 v[8:9], s[44:45]
	v_mov_b64_e32 v[10:11], s[46:47]
	v_mov_b64_e32 v[12:13], s[48:49]
	v_mfma_f32_32x32x16_bf16 v[16:31], v[48:51], v[144:147], v[16:31]
	s_nop 15
	s_nop 7
	s_waitcnt vmcnt(0) lgkmcnt(0)
	s_barrier
	v_mov_b64_e32 v[14:15], s[50:51]
	v_max3_f32 v48, v32, v33, v16
	v_max3_f32 v49, v34, v35, v17
	s_add_i32 s37, s0, 0
	v_max3_f32 v48, v48, v18, v19
	v_max3_f32 v49, v49, v38, v39
	s_add_i32 s37, s37, 0x12000
	v_max3_f32 v48, v48, v36, v37
	v_max3_f32 v49, v49, v22, v23
	v_lshl_add_u32 v212, v216, 2, s37
	v_max3_f32 v48, v48, v20, v21
	v_max3_f32 v49, v49, v42, v43
	s_nop 0
	v_max3_f32 v48, v48, v40, v41
	v_max3_f32 v49, v49, v26, v27
	s_nop 0
	v_max3_f32 v48, v48, v24, v25
	v_max3_f32 v49, v49, v46, v47
	s_nop 0
	v_max3_f32 v48, v48, v44, v45
	v_max3_f32 v49, v49, v30, v31
	s_nop 0
	v_max3_f32 v48, v48, v28, v29
	s_nop 0
	v_max_f32_e32 v48, v48, v49
	s_nop 0
	v_mov_b32_e32 v49, v48
	s_nop 1
	v_permlane32_swap_b32_e32 v48, v49
	v_max_f32_e32 v48, v48, v49
	s_nop 0
	v_sub_f32_e32 v16, v16, v48
	v_sub_f32_e32 v17, v17, v48
	v_sub_f32_e32 v32, v32, v48
	v_sub_f32_e32 v33, v33, v48
	v_sub_f32_e32 v34, v34, v48
	v_sub_f32_e32 v18, v18, v48
	s_nop 0
	v_exp_f32_e32 v64, v16
	v_exp_f32_e32 v65, v17
	v_lshl_add_u64 v[16:17], v[204:205], 0, s[18:19]
	s_mov_b32 s0, m0
	s_mov_b32 m0, s26
	s_nop 0
	global_load_lds_dwordx4 v[16:17], off
	s_mov_b32 m0, s0
	v_lshl_add_u64 v[16:17], v[224:225], 0, s[58:59]
	s_add_i32 s0, s26, 0xa000
	s_mov_b32 s1, m0
	s_mov_b32 m0, s0
	s_nop 0
	global_load_lds_dwordx4 v[16:17], off
	s_mov_b32 m0, s1
	s_mov_b64 s[0:1], 0x20080
	v_lshl_add_u64 v[16:17], v[224:225], 0, s[0:1]
	s_add_i32 s0, s26, 0xc000
	s_mov_b32 s1, m0
	s_mov_b32 m0, s0
	s_nop 0
	global_load_lds_dwordx4 v[16:17], off
	s_mov_b32 m0, s1
	ds_read_b128 v[96:99], v214 offset:8192
	ds_read_b128 v[112:115], v214 offset:8704
	ds_read_b128 v[180:183], v214 offset:10240
	ds_read_b128 v[176:179], v214 offset:10752
	ds_read_b128 v[172:175], v214 offset:12288
	ds_read_b128 v[168:171], v214 offset:12800
	ds_read_b128 v[164:167], v214 offset:14336
	ds_read_b128 v[160:163], v214 offset:14848
	v_sub_f32_e32 v35, v35, v48
	v_sub_f32_e32 v19, v19, v48
	v_sub_f32_e32 v36, v36, v48
	v_sub_f32_e32 v20, v20, v48
	v_sub_f32_e32 v37, v37, v48
	v_sub_f32_e32 v21, v21, v48
	v_sub_f32_e32 v38, v38, v48
	v_sub_f32_e32 v22, v22, v48
	v_sub_f32_e32 v39, v39, v48
	v_sub_f32_e32 v23, v23, v48
	v_sub_f32_e32 v40, v40, v48
	v_sub_f32_e32 v24, v24, v48
	v_sub_f32_e32 v41, v41, v48
	v_sub_f32_e32 v25, v25, v48
	v_sub_f32_e32 v42, v42, v48
	v_sub_f32_e32 v26, v26, v48
	v_sub_f32_e32 v43, v43, v48
	v_sub_f32_e32 v27, v27, v48
	v_sub_f32_e32 v44, v44, v48
	v_sub_f32_e32 v28, v28, v48
	v_sub_f32_e32 v45, v45, v48
	v_sub_f32_e32 v29, v29, v48
	v_sub_f32_e32 v46, v46, v48
	v_sub_f32_e32 v30, v30, v48
	v_sub_f32_e32 v47, v47, v48
	v_sub_f32_e32 v31, v31, v48
	v_exp_f32_e32 v80, v32
	v_exp_f32_e32 v81, v33
	v_exp_f32_e32 v82, v34
	v_exp_f32_e32 v83, v35
	v_exp_f32_e32 v84, v36
	v_exp_f32_e32 v85, v37
	v_exp_f32_e32 v86, v38
	v_exp_f32_e32 v87, v39
	v_exp_f32_e32 v88, v40
	v_exp_f32_e32 v89, v41
	v_exp_f32_e32 v90, v42
	v_exp_f32_e32 v91, v43
	v_exp_f32_e32 v92, v44
	v_exp_f32_e32 v93, v45
	v_exp_f32_e32 v94, v46
	v_exp_f32_e32 v95, v47
	v_exp_f32_e32 v66, v18
	v_exp_f32_e32 v67, v19
	v_exp_f32_e32 v68, v20
	v_exp_f32_e32 v69, v21
	v_exp_f32_e32 v70, v22
	v_exp_f32_e32 v71, v23
	v_exp_f32_e32 v72, v24
	v_exp_f32_e32 v73, v25
	v_exp_f32_e32 v74, v26
	v_exp_f32_e32 v75, v27
	v_exp_f32_e32 v76, v28
	v_exp_f32_e32 v77, v29
	v_exp_f32_e32 v78, v30
	v_exp_f32_e32 v79, v31
	s_waitcnt vmcnt(3) lgkmcnt(0)
	s_barrier
	s_mov_b64 s[0:1], 0x60080
	v_add_f32_e32 v222, v209, v48
	v_lshl_add_u64 v[206:207], v[224:225], 0, s[0:1]
	s_mov_b64 s[0:1], 0xa0000
	v_mov_b64_e32 v[62:63], v[14:15]
	v_mov_b64_e32 v[46:47], v[14:15]
	v_mov_b64_e32 v[30:31], v[14:15]
	v_lshl_add_u64 v[230:231], v[204:205], 0, s[0:1]
	v_mov_b64_e32 v[60:61], v[12:13]
	v_mov_b64_e32 v[58:59], v[10:11]
	v_mov_b64_e32 v[56:57], v[8:9]
	v_mov_b64_e32 v[54:55], v[6:7]
	v_mov_b64_e32 v[52:53], v[4:5]
	v_mov_b64_e32 v[50:51], v[2:3]
	v_mov_b64_e32 v[48:49], v[0:1]
	v_mov_b64_e32 v[44:45], v[12:13]
	v_mov_b64_e32 v[42:43], v[10:11]
	v_mov_b64_e32 v[40:41], v[8:9]
	v_mov_b64_e32 v[38:39], v[6:7]
	v_mov_b64_e32 v[36:37], v[4:5]
	v_mov_b64_e32 v[34:35], v[2:3]
	v_mov_b64_e32 v[32:33], v[0:1]
	v_mov_b64_e32 v[28:29], v[12:13]
	v_mov_b64_e32 v[26:27], v[10:11]
	v_mov_b64_e32 v[24:25], v[8:9]
	v_mov_b64_e32 v[22:23], v[6:7]
	v_mov_b64_e32 v[20:21], v[4:5]
	v_mov_b64_e32 v[18:19], v[2:3]
	v_mov_b64_e32 v[16:17], v[0:1]
	v_sub_f32_e32 v236, 0, v222
	v_sub_f32_e32 v237, 0, v222
	v_sub_f32_e32 v238, 0, v222
	v_sub_f32_e32 v239, 0, v222
	v_sub_f32_e32 v240, 0, v222
	v_sub_f32_e32 v241, 0, v222
	v_sub_f32_e32 v242, 0, v222
	v_sub_f32_e32 v243, 0, v222
	v_sub_f32_e32 v244, 0, v222
	v_sub_f32_e32 v245, 0, v222
	v_sub_f32_e32 v246, 0, v222
	v_sub_f32_e32 v247, 0, v222
	v_sub_f32_e32 v248, 0, v222
	v_sub_f32_e32 v249, 0, v222
	v_sub_f32_e32 v250, 0, v222
	v_sub_f32_e32 v251, 0, v222
	v_readfirstlane_b32 s98, v230
	v_readfirstlane_b32 s99, v231
	v_readfirstlane_b32 s86, v228
	v_readfirstlane_b32 s87, v229
	v_readfirstlane_b32 s90, v206
	v_readfirstlane_b32 s91, v207
	s_nop 1
	v_subrev_u32_e32 v230, s98, v230
	v_subrev_u32_e32 v228, s86, v228
	v_subrev_u32_e32 v206, s90, v206
	v_mov_b32_e32 v207, 0
	s_add_u32 s98, s98, 0xfffe0000
	s_addc_u32 s99, s99, -1
	s_add_u32 s86, s86, 0xfffe0000
	s_addc_u32 s87, s87, -1
	s_add_u32 s90, s90, 0xfffe0000
	s_addc_u32 s91, s91, -1
	s_cmp_lt_u32 s75, 4
	s_cbranch_scc1 .Lattn_prio_skip
	s_setprio 1
.Lattn_prio_skip:
.LBB0_842:
	s_lshl_b32 s0, s36, 1
	v_add_u32_e32 v200, s0, v211
	ds_read_b64_tr_b16 v[196:197], v200 offset:24576
	ds_read_b64_tr_b16 v[198:199], v200 offset:25088
	v_add_f32_e32 v100, v80, v81
	v_add_f32_e32 v100, v82, v100
	v_add_f32_e32 v100, v83, v100
	v_add_f32_e32 v100, v84, v100
	v_add_f32_e32 v116, v85, v100
	s_waitcnt lgkmcnt(9)
	v_mfma_f32_32x32x16_bf16 v[96:111], v[96:99], v[156:159], v[236:251]
	v_cvt_pk_bf16_f32 v140, v80, v81
	v_cvt_pk_bf16_f32 v141, v82, v83
	ds_read_b64_tr_b16 v[188:189], v200 offset:28672
	ds_read_b64_tr_b16 v[190:191], v200 offset:29184
	v_add_f32_e32 v80, v86, v116
	v_add_f32_e32 v80, v87, v80
	v_add_f32_e32 v80, v88, v80
	v_add_f32_e32 v80, v89, v80
	v_cvt_pk_bf16_f32 v142, v84, v85
	v_cvt_pk_bf16_f32 v143, v86, v87
	s_waitcnt lgkmcnt(10)
	v_mfma_f32_32x32x16_bf16 v[112:127], v[112:115], v[156:159], v[236:251]
	ds_read_b64_tr_b16 v[184:185], v200 offset:25600
	ds_read_b64_tr_b16 v[186:187], v200 offset:26112
	s_waitcnt lgkmcnt(11)
	v_mfma_f32_32x32x16_bf16 v[96:111], v[180:183], v[152:155], v[96:111]
	v_add_f32_e32 v80, v90, v80
	v_add_f32_e32 v80, v91, v80
	v_add_f32_e32 v80, v92, v80
	v_add_f32_e32 v80, v93, v80
	v_cvt_pk_bf16_f32 v136, v88, v89
	v_cvt_pk_bf16_f32 v137, v90, v91
	ds_read_b64_tr_b16 v[180:181], v200 offset:29696
	ds_read_b64_tr_b16 v[182:183], v200 offset:30208
	v_add_f32_e32 v80, v94, v80
	v_add_f32_e32 v80, v95, v80
	v_add_f32_e32 v80, v64, v80
	v_add_f32_e32 v80, v65, v80
	v_cvt_pk_bf16_f32 v138, v92, v93
	v_cvt_pk_bf16_f32 v139, v94, v95
	s_waitcnt lgkmcnt(12)
	v_mfma_f32_32x32x16_bf16 v[112:127], v[176:179], v[152:155], v[112:127]
	ds_read_b64_tr_b16 v[192:193], v200 offset:26624
	ds_read_b64_tr_b16 v[194:195], v200 offset:27136
	s_waitcnt lgkmcnt(13)
	v_mfma_f32_32x32x16_bf16 v[96:111], v[172:175], v[148:151], v[96:111]
	v_add_f32_e32 v80, v66, v80
	v_add_f32_e32 v80, v67, v80
	v_add_f32_e32 v80, v68, v80
	v_add_f32_e32 v80, v69, v80
	v_cvt_pk_bf16_f32 v132, v64, v65
	v_cvt_pk_bf16_f32 v133, v66, v67
	ds_read_b64_tr_b16 v[172:173], v200 offset:30720
	ds_read_b64_tr_b16 v[174:175], v200 offset:31232
	v_add_f32_e32 v64, v70, v80
	v_add_f32_e32 v64, v71, v64
	v_add_f32_e32 v64, v72, v64
	v_add_f32_e32 v64, v73, v64
	v_cvt_pk_bf16_f32 v134, v68, v69
	v_cvt_pk_bf16_f32 v135, v70, v71
	s_waitcnt lgkmcnt(14)
	v_mfma_f32_32x32x16_bf16 v[112:127], v[168:171], v[148:151], v[112:127]
	ds_read_b64_tr_b16 v[168:169], v200 offset:27648
	ds_read_b64_tr_b16 v[170:171], v200 offset:28160
	s_waitcnt lgkmcnt(14)
	v_mfma_f32_32x32x16_bf16 v[96:111], v[164:167], v[144:147], v[96:111]
	v_add_f32_e32 v64, v74, v64
	v_add_f32_e32 v64, v75, v64
	v_add_f32_e32 v64, v76, v64
	v_add_f32_e32 v64, v77, v64
	v_cvt_pk_bf16_f32 v128, v72, v73
	v_cvt_pk_bf16_f32 v129, v74, v75
	ds_read_b64_tr_b16 v[176:177], v200 offset:31744
	ds_read_b64_tr_b16 v[178:179], v200 offset:32256
	v_add_f32_e32 v64, v78, v64
	v_mfma_f32_32x32x16_bf16 v[112:127], v[160:163], v[144:147], v[112:127]
	v_add_f32_e32 v160, v79, v64
	v_cvt_pk_bf16_f32 v130, v76, v77
	v_cvt_pk_bf16_f32 v131, v78, v79
	s_add_i32 s0, s23, s26
	s_mov_b32 s1, m0
	s_mov_b32 m0, s0
	s_nop 0
	global_load_lds_dwordx4 v230, s[98:99]
	s_add_u32 s98, s98, 0x20000
	s_addc_u32 s99, s99, 0
	s_mov_b32 m0, s1
	s_lshl_b32 s0, s22, 1
	s_add_i32 s0, s0, s27
	s_mov_b32 s1, m0
	s_mov_b32 m0, s0
	s_nop 0
	global_load_lds_dwordx4 v228, s[86:87]
	s_add_u32 s86, s86, 0x20000
	s_addc_u32 s87, s87, 0
	s_mov_b32 m0, s1
	s_addk_i32 s0, 0x2000
	s_mov_b32 s1, m0
	s_mov_b32 m0, s0
	s_nop 0
	global_load_lds_dwordx4 v206, s[90:91]
	s_add_u32 s90, s90, 0x20000
	s_addc_u32 s91, s91, 0
	s_mov_b32 m0, s1
	v_max_f32_e32 v80, v96, v97
	v_max3_f32 v81, v98, v99, v113
	v_max3_f32 v80, v80, v112, v114
	v_max3_f32 v80, v80, v115, v100
	v_max3_f32 v81, v81, v102, v103
	v_max3_f32 v80, v80, v101, v116
	v_max3_f32 v81, v81, v118, v119
	v_max3_f32 v80, v80, v117, v104
	v_max3_f32 v81, v81, v106, v107
	v_max3_f32 v80, v80, v105, v120
	v_max3_f32 v81, v81, v122, v123
	v_max3_f32 v80, v80, v121, v108
	v_max3_f32 v81, v81, v110, v111
	v_max3_f32 v80, v80, v109, v124
	v_max3_f32 v81, v81, v126, v127
	v_max3_f32 v80, v80, v125, v81
	v_mov_b32_e32 v81, v80
	s_nop 1
	v_permlane32_swap_b32_e32 v80, v81
	v_max_f32_e32 v80, v80, v81
	v_cmp_lt_f32_e32 vcc, s56, v80
	s_cmp_lg_u64 vcc, 0
	v_add_f32_e32 v215, v215, v160
	s_cselect_b64 s[0:1], -1, 0
	s_cbranch_vccnz .LBB0_850
.LBB0_843:
	s_waitcnt lgkmcnt(14)
	v_mfma_f32_32x32x16_bf16 v[0:15], v[140:143], v[196:199], v[0:15]
	v_exp_f32_e32 v80, v96
	v_exp_f32_e32 v81, v97
	v_exp_f32_e32 v82, v98
	v_exp_f32_e32 v83, v99
	v_exp_f32_e32 v64, v112
	v_exp_f32_e32 v65, v113
	s_waitcnt lgkmcnt(12)
	v_mfma_f32_32x32x16_bf16 v[48:63], v[140:143], v[188:191], v[48:63]
	v_exp_f32_e32 v66, v114
	v_exp_f32_e32 v67, v115
	v_exp_f32_e32 v84, v100
	v_exp_f32_e32 v85, v101
	v_exp_f32_e32 v86, v102
	v_exp_f32_e32 v87, v103
	ds_read_b64_tr_b16 v[100:101], v200 offset:32768
	ds_read_b64_tr_b16 v[102:103], v200 offset:33280
	s_waitcnt lgkmcnt(12)
	v_mfma_f32_32x32x16_bf16 v[0:15], v[136:139], v[184:187], v[0:15]
	v_exp_f32_e32 v88, v104
	v_exp_f32_e32 v89, v105
	v_exp_f32_e32 v90, v106
	v_exp_f32_e32 v91, v107
	ds_read_b64_tr_b16 v[104:105], v200 offset:33792
	ds_read_b64_tr_b16 v[106:107], v200 offset:34304
	s_waitcnt lgkmcnt(12)
	v_mfma_f32_32x32x16_bf16 v[48:63], v[136:139], v[180:183], v[48:63]
	v_exp_f32_e32 v92, v108
	v_exp_f32_e32 v93, v109
	v_exp_f32_e32 v94, v110
	v_exp_f32_e32 v95, v111
	ds_read_b64_tr_b16 v[108:109], v200 offset:36864
	ds_read_b64_tr_b16 v[110:111], v200 offset:37376
	s_waitcnt lgkmcnt(12)
	v_mfma_f32_32x32x16_bf16 v[0:15], v[132:135], v[192:195], v[0:15]
	v_exp_f32_e32 v68, v116
	v_exp_f32_e32 v69, v117
	v_exp_f32_e32 v70, v118
	v_exp_f32_e32 v71, v119
	ds_read_b64_tr_b16 v[116:117], v200 offset:37888
	ds_read_b64_tr_b16 v[118:119], v200 offset:38400
	s_waitcnt lgkmcnt(12)
	v_mfma_f32_32x32x16_bf16 v[48:63], v[132:135], v[172:175], v[48:63]
	v_exp_f32_e32 v72, v120
	v_exp_f32_e32 v73, v121
	v_exp_f32_e32 v74, v122
	v_exp_f32_e32 v75, v123
	s_waitcnt lgkmcnt(10)
	v_mfma_f32_32x32x16_bf16 v[0:15], v[128:131], v[168:171], v[0:15]
	v_exp_f32_e32 v76, v124
	v_exp_f32_e32 v77, v125
	v_exp_f32_e32 v78, v126
	v_exp_f32_e32 v79, v127
	s_waitcnt lgkmcnt(8)
	v_mfma_f32_32x32x16_bf16 v[48:63], v[128:131], v[176:179], v[48:63]
	v_add_u32_e32 v120, s22, v214
	s_waitcnt lgkmcnt(6)
	v_mfma_f32_32x32x16_bf16 v[32:47], v[140:143], v[100:103], v[32:47]
	ds_read_b128 v[96:99], v120
	ds_read_b128 v[112:115], v120 offset:512
	s_waitcnt lgkmcnt(4)
	v_mfma_f32_32x32x16_bf16 v[16:31], v[140:143], v[108:111], v[16:31]
	ds_read_b64_tr_b16 v[100:101], v200 offset:34816
	ds_read_b64_tr_b16 v[102:103], v200 offset:35328
	ds_read_b64_tr_b16 v[108:109], v200 offset:38912
	ds_read_b64_tr_b16 v[110:111], v200 offset:39424
	v_mfma_f32_32x32x16_bf16 v[32:47], v[136:139], v[104:107], v[32:47]
	s_waitcnt lgkmcnt(6)
	v_mfma_f32_32x32x16_bf16 v[16:31], v[136:139], v[116:119], v[16:31]
	ds_read_b64_tr_b16 v[104:105], v200 offset:35840
	ds_read_b64_tr_b16 v[106:107], v200 offset:36352
	ds_read_b64_tr_b16 v[116:117], v200 offset:39936
	ds_read_b64_tr_b16 v[118:119], v200 offset:40448
	ds_read_b128 v[196:199], v120 offset:2048
	ds_read_b128 v[188:191], v120 offset:2560
	s_waitcnt lgkmcnt(8)
	v_mfma_f32_32x32x16_bf16 v[32:47], v[132:135], v[100:103], v[32:47]
	s_waitcnt lgkmcnt(6)
	v_mfma_f32_32x32x16_bf16 v[16:31], v[132:135], v[108:111], v[16:31]
	ds_read_b128 v[184:187], v120 offset:4096
	ds_read_b128 v[164:167], v120 offset:4608
	s_waitcnt lgkmcnt(6)
	v_mfma_f32_32x32x16_bf16 v[32:47], v[128:131], v[104:107], v[32:47]
	ds_read_b128 v[180:183], v120 offset:6144
	ds_read_b128 v[160:163], v120 offset:6656
	s_waitcnt lgkmcnt(6)
	v_mfma_f32_32x32x16_bf16 v[16:31], v[128:131], v[116:119], v[16:31]
	s_waitcnt vmcnt(3) lgkmcnt(0)
	s_barrier
	s_andn2_b64 vcc, exec, s[0:1]
	s_cbranch_vccnz .LBB0_845
	s_waitcnt lgkmcnt(0)
	v_add_u32_e32 v116, s37, v221
	ds_read_b128 v[100:103], v116 offset:96
	ds_read_b128 v[104:107], v116 offset:64
	ds_read_b128 v[108:111], v116 offset:32
	ds_read_b128 v[116:119], v116
	s_waitcnt lgkmcnt(3)
	v_pk_mul_f32 v[12:13], v[12:13], v[100:101]
	s_waitcnt lgkmcnt(2)
	v_pk_mul_f32 v[8:9], v[8:9], v[104:105]
	s_waitcnt lgkmcnt(1)
	v_pk_mul_f32 v[4:5], v[4:5], v[108:109]
	v_pk_mul_f32 v[14:15], v[14:15], v[102:103]
	v_pk_mul_f32 v[10:11], v[10:11], v[106:107]
	v_pk_mul_f32 v[6:7], v[6:7], v[110:111]
	s_waitcnt lgkmcnt(0)
	v_pk_mul_f32 v[2:3], v[2:3], v[118:119]
	v_pk_mul_f32 v[0:1], v[0:1], v[116:117]
	v_pk_mul_f32 v[60:61], v[60:61], v[100:101]
	v_pk_mul_f32 v[56:57], v[56:57], v[104:105]
	v_pk_mul_f32 v[52:53], v[52:53], v[108:109]
	v_pk_mul_f32 v[62:63], v[62:63], v[102:103]
	v_pk_mul_f32 v[58:59], v[58:59], v[106:107]
	v_pk_mul_f32 v[54:55], v[54:55], v[110:111]
	v_pk_mul_f32 v[50:51], v[50:51], v[118:119]
	v_pk_mul_f32 v[48:49], v[48:49], v[116:117]
	v_pk_mul_f32 v[44:45], v[44:45], v[100:101]
	v_pk_mul_f32 v[40:41], v[40:41], v[104:105]
	v_pk_mul_f32 v[36:37], v[36:37], v[108:109]
	v_pk_mul_f32 v[46:47], v[46:47], v[102:103]
	v_pk_mul_f32 v[42:43], v[42:43], v[106:107]
	v_pk_mul_f32 v[38:39], v[38:39], v[110:111]
	v_pk_mul_f32 v[34:35], v[34:35], v[118:119]
	v_pk_mul_f32 v[32:33], v[32:33], v[116:117]
	v_pk_mul_f32 v[28:29], v[28:29], v[100:101]
	v_pk_mul_f32 v[24:25], v[24:25], v[104:105]
	v_pk_mul_f32 v[20:21], v[20:21], v[108:109]
	v_pk_mul_f32 v[30:31], v[30:31], v[102:103]
	v_pk_mul_f32 v[26:27], v[26:27], v[106:107]
	v_pk_mul_f32 v[22:23], v[22:23], v[110:111]
	v_pk_mul_f32 v[18:19], v[18:19], v[118:119]
	v_pk_mul_f32 v[16:17], v[16:17], v[116:117]
.LBB0_845:
	s_add_i32 s0, s22, 0x2000
	s_cmpk_lg_i32 s22, 0x4000
	s_cselect_b32 s24, s0, 0
	s_lshl_b32 s0, s23, 1
	v_add_u32_e32 v255, s0, v211
	ds_read_b64_tr_b16 v[200:201], v255 offset:24576
	ds_read_b64_tr_b16 v[202:203], v255 offset:25088
	v_add_f32_e32 v100, v80, v81
	v_add_f32_e32 v100, v82, v100
	v_add_f32_e32 v100, v83, v100
	v_add_f32_e32 v100, v84, v100
	v_add_f32_e32 v116, v85, v100
	v_mfma_f32_32x32x16_bf16 v[96:111], v[96:99], v[156:159], v[236:251]
	v_cvt_pk_bf16_f32 v140, v80, v81
	v_cvt_pk_bf16_f32 v141, v82, v83
	ds_read_b64_tr_b16 v[176:177], v255 offset:28672
	ds_read_b64_tr_b16 v[178:179], v255 offset:29184
	v_add_f32_e32 v80, v86, v116
	v_add_f32_e32 v80, v87, v80
	v_add_f32_e32 v80, v88, v80
	v_add_f32_e32 v80, v89, v80
	v_cvt_pk_bf16_f32 v142, v84, v85
	v_cvt_pk_bf16_f32 v143, v86, v87
	v_mfma_f32_32x32x16_bf16 v[112:127], v[112:115], v[156:159], v[236:251]
	ds_read_b64_tr_b16 v[168:169], v255 offset:25600
	ds_read_b64_tr_b16 v[170:171], v255 offset:26112
	v_mfma_f32_32x32x16_bf16 v[96:111], v[196:199], v[152:155], v[96:111]
	v_add_f32_e32 v80, v90, v80
	v_add_f32_e32 v80, v91, v80
	v_add_f32_e32 v80, v92, v80
	v_add_f32_e32 v80, v93, v80
	v_cvt_pk_bf16_f32 v136, v88, v89
	v_cvt_pk_bf16_f32 v137, v90, v91
	ds_read_b64_tr_b16 v[172:173], v255 offset:29696
	ds_read_b64_tr_b16 v[174:175], v255 offset:30208
	v_add_f32_e32 v80, v94, v80
	v_add_f32_e32 v80, v95, v80
	v_add_f32_e32 v80, v64, v80
	v_add_f32_e32 v80, v65, v80
	v_cvt_pk_bf16_f32 v138, v92, v93
	v_cvt_pk_bf16_f32 v139, v94, v95
	v_mfma_f32_32x32x16_bf16 v[112:127], v[188:191], v[152:155], v[112:127]
	ds_read_b64_tr_b16 v[196:197], v255 offset:26624
	ds_read_b64_tr_b16 v[198:199], v255 offset:27136
	v_mfma_f32_32x32x16_bf16 v[96:111], v[184:187], v[148:151], v[96:111]
	v_add_f32_e32 v80, v66, v80
	v_add_f32_e32 v80, v67, v80
	v_add_f32_e32 v80, v68, v80
	v_add_f32_e32 v80, v69, v80
	v_cvt_pk_bf16_f32 v132, v64, v65
	v_cvt_pk_bf16_f32 v133, v66, v67
	ds_read_b64_tr_b16 v[184:185], v255 offset:30720
	ds_read_b64_tr_b16 v[186:187], v255 offset:31232
	v_add_f32_e32 v64, v70, v80
	v_add_f32_e32 v64, v71, v64
	v_add_f32_e32 v64, v72, v64
	v_add_f32_e32 v64, v73, v64
	v_cvt_pk_bf16_f32 v134, v68, v69
	v_cvt_pk_bf16_f32 v135, v70, v71
	v_mfma_f32_32x32x16_bf16 v[112:127], v[164:167], v[148:151], v[112:127]
	ds_read_b64_tr_b16 v[188:189], v255 offset:27648
	ds_read_b64_tr_b16 v[190:191], v255 offset:28160
	v_mfma_f32_32x32x16_bf16 v[96:111], v[180:183], v[144:147], v[96:111]
	v_add_f32_e32 v64, v74, v64
	v_add_f32_e32 v64, v75, v64
	v_add_f32_e32 v64, v76, v64
	v_add_f32_e32 v64, v77, v64
	v_cvt_pk_bf16_f32 v128, v72, v73
	v_cvt_pk_bf16_f32 v129, v74, v75
	ds_read_b64_tr_b16 v[192:193], v255 offset:31744
	ds_read_b64_tr_b16 v[194:195], v255 offset:32256
	v_add_f32_e32 v64, v78, v64
	v_mfma_f32_32x32x16_bf16 v[112:127], v[160:163], v[144:147], v[112:127]
	v_add_f32_e32 v160, v79, v64
	v_cvt_pk_bf16_f32 v130, v76, v77
	v_cvt_pk_bf16_f32 v131, v78, v79
	s_add_i32 s0, s22, s26
	s_mov_b32 s1, m0
	s_mov_b32 m0, s0
	s_nop 0
	global_load_lds_dwordx4 v230, s[98:99]
	s_add_u32 s98, s98, 0x20000
	s_addc_u32 s99, s99, 0
	s_mov_b32 m0, s1
	s_lshl_b32 s0, s24, 1
	s_add_i32 s0, s0, s27
	s_mov_b32 s1, m0
	s_mov_b32 m0, s0
	s_nop 0
	global_load_lds_dwordx4 v228, s[86:87]
	s_add_u32 s86, s86, 0x20000
	s_addc_u32 s87, s87, 0
	s_mov_b32 m0, s1
	s_addk_i32 s0, 0x2000
	s_mov_b32 s1, m0
	s_mov_b32 m0, s0
	s_nop 0
	global_load_lds_dwordx4 v206, s[90:91]
	s_add_u32 s90, s90, 0x20000
	s_addc_u32 s91, s91, 0
	s_mov_b32 m0, s1
	v_max_f32_e32 v80, v96, v97
	v_max3_f32 v81, v98, v99, v113
	v_max3_f32 v80, v80, v112, v114
	v_max3_f32 v80, v80, v115, v100
	v_max3_f32 v81, v81, v102, v103
	v_max3_f32 v80, v80, v101, v116
	v_max3_f32 v81, v81, v118, v119
	v_max3_f32 v80, v80, v117, v104
	v_max3_f32 v81, v81, v106, v107
	v_max3_f32 v80, v80, v105, v120
	v_max3_f32 v81, v81, v122, v123
	v_max3_f32 v80, v80, v121, v108
	v_max3_f32 v81, v81, v110, v111
	v_max3_f32 v80, v80, v109, v124
	v_max3_f32 v81, v81, v126, v127
	v_max3_f32 v80, v80, v125, v81
	v_mov_b32_e32 v81, v80
	s_nop 1
	v_permlane32_swap_b32_e32 v80, v81
	v_max_f32_e32 v80, v80, v81
	v_cmp_lt_f32_e32 vcc, s56, v80
	s_cmp_lg_u64 vcc, 0
	v_add_f32_e32 v215, v215, v160
	s_cselect_b64 s[0:1], -1, 0
	s_cbranch_vccnz .LBB0_853
.LBB0_846:
	s_waitcnt lgkmcnt(14)
	v_mfma_f32_32x32x16_bf16 v[0:15], v[140:143], v[200:203], v[0:15]
	v_exp_f32_e32 v80, v96
	v_exp_f32_e32 v81, v97
	v_exp_f32_e32 v82, v98
	v_exp_f32_e32 v83, v99
	v_exp_f32_e32 v64, v112
	v_exp_f32_e32 v65, v113
	s_waitcnt lgkmcnt(12)
	v_mfma_f32_32x32x16_bf16 v[48:63], v[140:143], v[176:179], v[48:63]
	v_exp_f32_e32 v66, v114
	v_exp_f32_e32 v67, v115
	v_exp_f32_e32 v84, v100
	v_exp_f32_e32 v85, v101
	v_exp_f32_e32 v86, v102
	v_exp_f32_e32 v87, v103
	ds_read_b64_tr_b16 v[100:101], v255 offset:32768
	ds_read_b64_tr_b16 v[102:103], v255 offset:33280
	s_waitcnt lgkmcnt(12)
	v_mfma_f32_32x32x16_bf16 v[0:15], v[136:139], v[168:171], v[0:15]
	v_exp_f32_e32 v88, v104
	v_exp_f32_e32 v89, v105
	v_exp_f32_e32 v90, v106
	v_exp_f32_e32 v91, v107
	ds_read_b64_tr_b16 v[104:105], v255 offset:33792
	ds_read_b64_tr_b16 v[106:107], v255 offset:34304
	s_waitcnt lgkmcnt(12)
	v_mfma_f32_32x32x16_bf16 v[48:63], v[136:139], v[172:175], v[48:63]
	v_exp_f32_e32 v92, v108
	v_exp_f32_e32 v93, v109
	v_exp_f32_e32 v94, v110
	v_exp_f32_e32 v95, v111
	ds_read_b64_tr_b16 v[108:109], v255 offset:36864
	ds_read_b64_tr_b16 v[110:111], v255 offset:37376
	s_waitcnt lgkmcnt(12)
	v_mfma_f32_32x32x16_bf16 v[0:15], v[132:135], v[196:199], v[0:15]
	v_exp_f32_e32 v68, v116
	v_exp_f32_e32 v69, v117
	v_exp_f32_e32 v70, v118
	v_exp_f32_e32 v71, v119
	ds_read_b64_tr_b16 v[116:117], v255 offset:37888
	ds_read_b64_tr_b16 v[118:119], v255 offset:38400
	s_waitcnt lgkmcnt(12)
	v_mfma_f32_32x32x16_bf16 v[48:63], v[132:135], v[184:187], v[48:63]
	v_exp_f32_e32 v72, v120
	v_exp_f32_e32 v73, v121
	v_exp_f32_e32 v74, v122
	v_exp_f32_e32 v75, v123
	s_waitcnt lgkmcnt(10)
	v_mfma_f32_32x32x16_bf16 v[0:15], v[128:131], v[188:191], v[0:15]
	v_exp_f32_e32 v76, v124
	v_exp_f32_e32 v77, v125
	v_exp_f32_e32 v78, v126
	v_exp_f32_e32 v79, v127
	s_waitcnt lgkmcnt(8)
	v_mfma_f32_32x32x16_bf16 v[48:63], v[128:131], v[192:195], v[48:63]
	v_add_u32_e32 v120, s24, v214
	s_waitcnt lgkmcnt(6)
	v_mfma_f32_32x32x16_bf16 v[32:47], v[140:143], v[100:103], v[32:47]
	ds_read_b128 v[96:99], v120
	ds_read_b128 v[112:115], v120 offset:512
	s_waitcnt lgkmcnt(4)
	v_mfma_f32_32x32x16_bf16 v[16:31], v[140:143], v[108:111], v[16:31]
	ds_read_b64_tr_b16 v[100:101], v255 offset:34816
	ds_read_b64_tr_b16 v[102:103], v255 offset:35328
	ds_read_b64_tr_b16 v[108:109], v255 offset:38912
	ds_read_b64_tr_b16 v[110:111], v255 offset:39424
	v_mfma_f32_32x32x16_bf16 v[32:47], v[136:139], v[104:107], v[32:47]
	s_waitcnt lgkmcnt(6)
	v_mfma_f32_32x32x16_bf16 v[16:31], v[136:139], v[116:119], v[16:31]
	ds_read_b64_tr_b16 v[104:105], v255 offset:35840
	ds_read_b64_tr_b16 v[106:107], v255 offset:36352
	ds_read_b64_tr_b16 v[116:117], v255 offset:39936
	ds_read_b64_tr_b16 v[118:119], v255 offset:40448
	ds_read_b128 v[180:183], v120 offset:2048
	ds_read_b128 v[176:179], v120 offset:2560
	s_waitcnt lgkmcnt(8)
	v_mfma_f32_32x32x16_bf16 v[32:47], v[132:135], v[100:103], v[32:47]
	s_waitcnt lgkmcnt(6)
	v_mfma_f32_32x32x16_bf16 v[16:31], v[132:135], v[108:111], v[16:31]
	ds_read_b128 v[172:175], v120 offset:4096
	ds_read_b128 v[168:171], v120 offset:4608
	s_waitcnt lgkmcnt(6)
	v_mfma_f32_32x32x16_bf16 v[32:47], v[128:131], v[104:107], v[32:47]
	ds_read_b128 v[164:167], v120 offset:6144
	ds_read_b128 v[160:163], v120 offset:6656
	s_waitcnt lgkmcnt(6)
	v_mfma_f32_32x32x16_bf16 v[16:31], v[128:131], v[116:119], v[16:31]
	s_waitcnt vmcnt(3) lgkmcnt(0)
	s_barrier
	s_andn2_b64 vcc, exec, s[0:1]
	s_cbranch_vccnz .LBB0_848
	s_waitcnt lgkmcnt(0)
	v_add_u32_e32 v116, s37, v221
	ds_read_b128 v[100:103], v116 offset:96
	ds_read_b128 v[104:107], v116 offset:64
	ds_read_b128 v[108:111], v116 offset:32
	ds_read_b128 v[116:119], v116
	s_waitcnt lgkmcnt(3)
	v_pk_mul_f32 v[12:13], v[12:13], v[100:101]
	s_waitcnt lgkmcnt(2)
	v_pk_mul_f32 v[8:9], v[8:9], v[104:105]
	s_waitcnt lgkmcnt(1)
	v_pk_mul_f32 v[4:5], v[4:5], v[108:109]
	v_pk_mul_f32 v[14:15], v[14:15], v[102:103]
	v_pk_mul_f32 v[10:11], v[10:11], v[106:107]
	v_pk_mul_f32 v[6:7], v[6:7], v[110:111]
	s_waitcnt lgkmcnt(0)
	v_pk_mul_f32 v[2:3], v[2:3], v[118:119]
	v_pk_mul_f32 v[0:1], v[0:1], v[116:117]
	v_pk_mul_f32 v[60:61], v[60:61], v[100:101]
	v_pk_mul_f32 v[56:57], v[56:57], v[104:105]
	v_pk_mul_f32 v[52:53], v[52:53], v[108:109]
	v_pk_mul_f32 v[62:63], v[62:63], v[102:103]
	v_pk_mul_f32 v[58:59], v[58:59], v[106:107]
	v_pk_mul_f32 v[54:55], v[54:55], v[110:111]
	v_pk_mul_f32 v[50:51], v[50:51], v[118:119]
	v_pk_mul_f32 v[48:49], v[48:49], v[116:117]
	v_pk_mul_f32 v[44:45], v[44:45], v[100:101]
	v_pk_mul_f32 v[40:41], v[40:41], v[104:105]
	v_pk_mul_f32 v[36:37], v[36:37], v[108:109]
	v_pk_mul_f32 v[46:47], v[46:47], v[102:103]
	v_pk_mul_f32 v[42:43], v[42:43], v[106:107]
	v_pk_mul_f32 v[38:39], v[38:39], v[110:111]
	v_pk_mul_f32 v[34:35], v[34:35], v[118:119]
	v_pk_mul_f32 v[32:33], v[32:33], v[116:117]
	v_pk_mul_f32 v[28:29], v[28:29], v[100:101]
	v_pk_mul_f32 v[24:25], v[24:25], v[104:105]
	v_pk_mul_f32 v[20:21], v[20:21], v[108:109]
	v_pk_mul_f32 v[30:31], v[30:31], v[102:103]
	v_pk_mul_f32 v[26:27], v[26:27], v[106:107]
	v_pk_mul_f32 v[22:23], v[22:23], v[110:111]
	v_pk_mul_f32 v[18:19], v[18:19], v[118:119]
	v_pk_mul_f32 v[16:17], v[16:17], v[116:117]
